# attnA: K/V LDS tile double-buffered, one barrier per key tile instead of two
# speedup vs baseline: 1.0240x; 1.0043x over previous
; __device__ __forceinline__ int get_tid() { int t = threadIdx.x; asm volatile("" : "+v"(t)); return t; }
; __device__ __forceinline__ void ld16_sc1(u32x4& v, const void* p) { asm volatile("global_load_dwordx4 %0, %1, off sc1" : "=v"(v) : "v"(p) : "memory"); }
; __device__ __forceinline__ void ld16_sc1(f32x4& v, const float* p) { asm volatile("global_load_dwordx4 %0, %1, off sc1" : "=v"(v) : "v"(p) : "memory"); }
;   __device__ __forceinline__ const bf16_t* kptr(int t, int row) const { return zs + (size_t)(kidx(t, row) * d + r) * ZW + kcol; }
;   __device__ __forceinline__ const bf16_t* vptr(int t, int row) const { return zs + (size_t)(kidx(t, row) * d + r) * ZW + vcol; }
;   __device__ __forceinline__ const bf16_t* kptr(int t, int row) const { return zs + (size_t)(krow(t) * 64 + row) * ZW + 1024 + hc; }
;   __device__ __forceinline__ const bf16_t* vptr(int t, int row) const { return zs + (size_t)(krow(t) * 64 + row) * ZW + 2048 + hc; }
; template <int DH, int KT, int NQT, bool PF, class Ctx>
; __device__ __forceinline__ void attn_item(unsigned char* smem, const Ctx& c) {
;   constexpr int LDK = DH + 8, CH = DH / 8, NCH = KT * CH / 256, NKS = DH / 32, NK4 = KT / 16, NKK = KT / 32, NDT = DH / 16;
;   bf16_t* sK = (bf16_t*)smem; bf16_t* sV = sK + KT * LDK;
;   const int tid = get_tid(), lane = tid & 63;
;   const int wid = __builtin_amdgcn_readfirstlane(tid >> 6);
;   const int l15 = lane & 15, quad = lane >> 4;
;   bf16x8 qf[NQT][NKS];
; #pragma unroll
;   for (int qt = 0; qt < NQT; ++qt) {
;     const bf16_t* qp = c.qptr(wid, qt * 16 + l15);
; #pragma unroll
;     for (int ks = 0; ks < NKS; ++ks) qf[qt][ks] = __builtin_bit_cast(bf16x8, ld_agent_u32x4(qp + ks * 32 + quad * 8));
;   }
;   f32x4 o[NQT][NDT];
;   float mrow[NQT], lrow[NQT];
; #pragma unroll
;   for (int qt = 0; qt < NQT; ++qt) {
;     mrow[qt] = -1e30f; lrow[qt] = 0.f;
; #pragma unroll
;     for (int dt = 0; dt < NDT; ++dt) o[qt][dt] = (f32x4){0.f, 0.f, 0.f, 0.f};
;   }
;   const int nt = c.ntiles();
;   u32x4 rk[NCH], rv[NCH];
;   if constexpr (PF) {
; #pragma unroll
;     for (int i = 0; i < NCH; ++i) {
;       const int ci = tid + 256 * i, row = ci / CH, ch = ci % CH;
;       ld16_sc1(rk[i], c.kptr(0, row) + ch * 8); ld16_sc1(rv[i], c.vptr(0, row) + ch * 8);
;     }
;   }
.LBB0_211:
	s_lshl_b32 s0, s7, 8
	s_add_i32 s0, s5, s0
	s_mul_hi_i32 s1, s0, 0x1800
	s_mulk_i32 s0, 0x1800
	s_add_u32 s0, s86, s0
	s_addc_u32 s1, s87, s1
	s_lshl_b32 s3, s4, 7
	s_add_u32 s0, s0, s3
	s_addc_u32 s1, s1, 0
	s_mul_i32 s12, s5, 0x1800
	s_mul_hi_i32 s3, s5, 0x1800
	s_add_u32 s5, s86, s12
	s_addc_u32 s7, s87, s3
	s_lshl_b32 s8, s4, 5
	s_and_b32 s8, s8, 0xffffff80
	v_mov_b32_e32 v14, v210
	s_add_u32 s8, s5, s8
	s_addc_u32 s9, s7, 0
	v_readfirstlane_b32 s5, v14
	v_bfe_u32 v24, v14, 4, 2
	v_and_b32_e32 v15, 15, v14
	s_andn2_b32 s5, s5, 63
	v_lshlrev_b32_e32 v188, 4, v24
	v_or_b32_e32 v12, s5, v15
	v_lshl_add_u64 v[0:1], s[0:1], 0, v[188:189]
	v_mad_i64_i32 v[2:3], s[10:11], v12, s97, v[0:1]
	global_load_dwordx2 v[4:5], v[2:3], off sc1
	global_load_dwordx2 v[6:7], v[2:3], off offset:8 sc1
	global_load_dwordx2 v[8:9], v[2:3], off offset:64 sc1
	global_load_dwordx2 v[10:11], v[2:3], off offset:72 sc1
	v_or_b32_e32 v2, 16, v12
	v_mad_i64_i32 v[198:199], s[10:11], v2, s97, 0
	v_mad_i64_i32 v[2:3], s[10:11], v2, s97, v[0:1]
	global_load_dwordx2 v[16:17], v[2:3], off sc1
	global_load_dwordx2 v[18:19], v[2:3], off offset:8 sc1
	global_load_dwordx2 v[20:21], v[2:3], off offset:64 sc1
	global_load_dwordx2 v[22:23], v[2:3], off offset:72 sc1
	v_or_b32_e32 v2, 32, v12
	v_mad_i64_i32 v[196:197], s[10:11], v2, s97, 0
	v_mad_i64_i32 v[2:3], s[10:11], v2, s97, v[0:1]
	global_load_dwordx2 v[28:29], v[2:3], off sc1
	global_load_dwordx2 v[30:31], v[2:3], off offset:8 sc1
	global_load_dwordx2 v[36:37], v[2:3], off offset:64 sc1
	global_load_dwordx2 v[38:39], v[2:3], off offset:72 sc1
	v_or_b32_e32 v2, 48, v12
	v_mad_i64_i32 v[0:1], s[10:11], v2, s97, v[0:1]
	global_load_dwordx2 v[40:41], v[0:1], off sc1
	global_load_dwordx2 v[42:43], v[0:1], off offset:8 sc1
	global_load_dwordx2 v[44:45], v[0:1], off offset:64 sc1
	global_load_dwordx2 v[46:47], v[0:1], off offset:72 sc1
	v_ashrrev_i32_e32 v0, 31, v14
	v_lshrrev_b32_e32 v0, 29, v0
	v_add_u32_e32 v0, v14, v0
	v_ashrrev_i32_e32 v25, 3, v0
	v_and_b32_e32 v0, -8, v0
	v_sub_u32_e32 v26, v14, v0
	v_mov_b64_e32 v[0:1], s[8:9]
	v_lshlrev_b32_e32 v202, 3, v26
	v_mad_i64_i32 v[200:201], s[10:11], v12, s97, 0
	v_mad_i64_i32 v[194:195], s[10:11], v2, s97, 0
	v_mad_i64_i32 v[2:3], s[8:9], v25, s97, v[0:1]
	v_ashrrev_i32_e32 v203, 31, v202
	v_lshl_add_u64 v[2:3], v[202:203], 1, v[2:3]
	s_mov_b64 s[10:11], 0x400
	s_mov_b64 s[14:15], 0x500
	v_lshl_add_u64 v[12:13], v[2:3], 0, s[10:11]
	global_load_dwordx4 v[56:59], v[12:13], off sc1
	v_lshl_add_u64 v[2:3], v[2:3], 0, s[14:15]
	global_load_dwordx4 v[60:63], v[2:3], off sc1
	v_add_u32_e32 v2, 0x100, v14
	v_ashrrev_i32_e32 v3, 31, v2
	v_lshrrev_b32_e32 v3, 29, v3
	v_add_u32_e32 v3, v2, v3
	v_ashrrev_i32_e32 v12, 3, v3
	v_and_b32_e32 v3, -8, v3
	v_sub_u32_e32 v13, v2, v3
	v_lshlrev_b32_e32 v204, 3, v13
	v_mad_i64_i32 v[0:1], s[8:9], v12, s97, v[0:1]
	v_ashrrev_i32_e32 v205, 31, v204
	s_lshl_b64 s[4:5], s[4:5], 5
	v_lshl_add_u64 v[0:1], v[204:205], 1, v[0:1]
	s_and_b32 s5, s5, 31
	s_and_b32 s4, s4, 0xffffff80
	v_lshl_add_u64 v[2:3], v[0:1], 0, s[10:11]
	global_load_dwordx4 v[72:75], v[2:3], off sc1
	v_lshl_add_u64 v[0:1], v[0:1], 0, s[14:15]
	s_add_u32 s4, s42, s4
	global_load_dwordx4 v[80:83], v[0:1], off sc1
	v_lshlrev_b32_e32 v1, 3, v14
	s_addc_u32 s5, s43, s5
	v_lshlrev_b32_e32 v219, 2, v24
	v_bfe_u32 v0, v14, 2, 2
	v_and_b32_e32 v2, 24, v1
	v_mul_lo_u32 v1, v25, s60
	s_add_u32 s4, s4, s12
	v_or_b32_e32 v0, v219, v0
	v_lshl_add_u32 v221, v26, 4, v1
	v_mul_lo_u32 v1, v12, s60
	s_addc_u32 s5, s5, s3
	v_lshl_add_u32 v222, v13, 4, v1
	v_mul_u32_u24_e32 v3, 0x90, v15
	v_mul_u32_u24_e32 v13, 0x90, v0
	v_mov_b64_e32 v[0:1], s[4:5]
	v_mov_b32_e32 v68, v189
	v_mov_b32_e32 v69, v189
	v_mov_b32_e32 v70, v189
	v_mov_b32_e32 v71, v189
	v_mad_i64_i32 v[206:207], s[4:5], v12, s97, v[0:1]
	v_mad_i64_i32 v[208:209], s[4:5], v25, s97, v[0:1]
	v_add_u32_e32 v188, v188, v3
	v_add_u32_e32 v224, v2, v13
	v_mov_b64_e32 v[86:87], v[70:71]
	v_mov_b64_e32 v[90:91], v[70:71]
	v_mov_b64_e32 v[94:95], v[70:71]
	v_mov_b64_e32 v[98:99], v[70:71]
	v_mov_b64_e32 v[102:103], v[70:71]
	v_mov_b64_e32 v[106:107], v[70:71]
	v_mov_b64_e32 v[110:111], v[70:71]
	v_mov_b64_e32 v[78:79], v[70:71]
	v_mov_b64_e32 v[64:65], v[68:69]
	v_mov_b64_e32 v[52:53], v[68:69]
	v_mov_b64_e32 v[48:49], v[68:69]
	s_waitcnt vmcnt(26)
	v_mov_b64_e32 v[32:33], v[68:69]
	v_mov_b64_e32 v[24:25], v[68:69]
	v_mov_b64_e32 v[12:13], v[68:69]
	v_mov_b64_e32 v[0:1], v[68:69]
	s_mov_b32 s7, 1
	s_mul_i32 s8, s6, 0x60000
	v_mov_b32_e32 v191, 0
	v_mov_b64_e32 v[232:233], v[68:69]
	v_mov_b64_e32 v[234:235], v[68:69]
	v_mov_b64_e32 v[236:237], v[68:69]
	v_mov_b64_e32 v[238:239], v[68:69]
	s_mov_b64 s[4:5], 0
	v_mov_b64_e32 v[84:85], v[68:69]
	v_mov_b64_e32 v[88:89], v[68:69]
	v_mov_b64_e32 v[92:93], v[68:69]
	v_mov_b64_e32 v[96:97], v[68:69]
	v_mov_b64_e32 v[100:101], v[68:69]
	v_mov_b64_e32 v[104:105], v[68:69]
	v_mov_b64_e32 v[108:109], v[68:69]
	v_mov_b64_e32 v[240:241], v[68:69]
	v_mov_b64_e32 v[242:243], v[68:69]
	v_mov_b64_e32 v[244:245], v[68:69]
	v_mov_b64_e32 v[246:247], v[68:69]
	v_mov_b32_e32 v249, 0xff800000
	v_mov_b32_e32 v193, 0
	v_mov_b32_e32 v218, 0
	v_mov_b32_e32 v225, 0
	v_mov_b64_e32 v[76:77], v[68:69]
	v_mov_b64_e32 v[66:67], v[70:71]
	v_mov_b64_e32 v[54:55], v[70:71]
	v_mov_b64_e32 v[50:51], v[70:71]
	v_mov_b64_e32 v[34:35], v[70:71]
	v_mov_b64_e32 v[26:27], v[70:71]
	v_mov_b64_e32 v[14:15], v[70:71]
	v_mov_b64_e32 v[2:3], v[70:71]
	s_barrier
	s_branch .LBB0_213

; __device__ __forceinline__ void ld16_sc1(u32x4& v, const void* p) { asm volatile("global_load_dwordx4 %0, %1, off sc1" : "=v"(v) : "v"(p) : "memory"); }
; __device__ __forceinline__ void ld16_sc1(f32x4& v, const float* p) { asm volatile("global_load_dwordx4 %0, %1, off sc1" : "=v"(v) : "v"(p) : "memory"); }
;   __device__ __forceinline__ const bf16_t* kptr(int t, int row) const { return zs + (size_t)(kidx(t, row) * d + r) * ZW + kcol; }
;   __device__ __forceinline__ const bf16_t* vptr(int t, int row) const { return zs + (size_t)(kidx(t, row) * d + r) * ZW + vcol; }
; template <int DH, int KT, int NQT, bool PF, class Ctx>
; __device__ __forceinline__ void attn_item(unsigned char* smem, const Ctx& c) {
;     ...
;   for (int t = 0; t < nt; ++t) {
;     __syncthreads();
;     if constexpr (PF) {
;       static_assert(!PF || NCH == 2 || NCH == 4, "wait lists below are written for two or four chunks per matrix");
;       if constexpr (NCH == 2) asm volatile("s_waitcnt vmcnt(0)" : "+v"(rk[0]), "+v"(rk[NCH - 1]), "+v"(rv[0]), "+v"(rv[NCH - 1]) :: "memory");
;       else asm volatile("s_waitcnt vmcnt(0)" : "+v"(rk[0]), "+v"(rk[1]), "+v"(rk[NCH - 2]), "+v"(rk[NCH - 1]), "+v"(rv[0]), "+v"(rv[1]), "+v"(rv[NCH - 2]), "+v"(rv[NCH - 1]) :: "memory");
; #pragma unroll
;       for (int i = 0; i < NCH; ++i) {
;         const int ci = tid + 256 * i, row = ci / CH, ch = ci % CH;
;         *(u32x4*)(sK + row * LDK + ch * 8) = rk[i]; *(u32x4*)(sV + row * LDK + ch * 8) = rv[i];
;       }
;     } else {
; #pragma unroll
;       for (int i = 0; i < NCH; ++i) {
;         const int ci = tid + 256 * i, row = ci / CH, ch = ci % CH;
;         *(u32x4*)(sK + row * LDK + ch * 8) = ld_agent_u32x4(c.kptr(t, row) + ch * 8);
;       }
; #pragma unroll
;       for (int i = 0; i < NCH; ++i) {
;         const int ci = tid + 256 * i, row = ci / CH, ch = ci % CH;
;         *(u32x4*)(sV + row * LDK + ch * 8) = ld_agent_u32x4(c.vptr(t, row) + ch * 8);
;       }
;     }
;     __syncthreads();
;     if constexpr (PF) {
;       if (t + 1 < nt) {
; #pragma unroll
;         for (int i = 0; i < NCH; ++i) {
;           const int ci = tid + 256 * i, row = ci / CH, ch = ci % CH;
;           ld16_sc1(rk[i], c.kptr(t + 1, row) + ch * 8); ld16_sc1(rv[i], c.vptr(t + 1, row) + ch * 8);
;         }
;       }
.LBB0_213:
	v_xor_b32_e32 v221, 0x8000, v221
	v_xor_b32_e32 v222, 0x8000, v222
	v_xor_b32_e32 v188, 0x8000, v188
	v_xor_b32_e32 v224, 0x8000, v224
	s_waitcnt vmcnt(0)
	s_cmp_ge_u32 s7, s6
	ds_write_b128 v221, v[56:59]
	ds_write_b128 v221, v[60:63] offset:9216
	ds_write_b128 v222, v[72:75]
	ds_write_b128 v222, v[80:83] offset:9216
	s_waitcnt lgkmcnt(0)
	s_barrier
	s_cbranch_scc1 .LBB0_215
	v_lshl_add_u64 v[56:57], v[208:209], 0, s[4:5]
	v_lshl_add_u64 v[60:61], v[202:203], 1, v[56:57]
	v_lshl_add_u64 v[56:57], v[60:61], 0, s[52:53]
	v_lshl_add_u64 v[72:73], v[206:207], 0, s[4:5]
	global_load_dwordx4 v[56:59], v[56:57], off sc1
	v_lshl_add_u64 v[60:61], v[60:61], 0, s[54:55]
	v_lshl_add_u64 v[80:81], v[204:205], 1, v[72:73]
	global_load_dwordx4 v[60:63], v[60:61], off sc1
	v_lshl_add_u64 v[72:73], v[80:81], 0, s[52:53]
	global_load_dwordx4 v[72:75], v[72:73], off sc1
	v_lshl_add_u64 v[80:81], v[80:81], 0, s[54:55]
	global_load_dwordx4 v[80:83], v[80:81], off sc1
